# main GEMM: no per-phase flips, static s_setprio 1 for waves 4-7 over the whole GEMM phase
# baseline (speedup 1.0000x reference)
; #define WAIT_V(n) asm volatile("s_waitcnt vmcnt(" #n ")" ::: "memory")
; #define BAR __builtin_amdgcn_s_barrier()
; #define STG(P, PTR, LD, O0) do { const bf16_t* _g = (PTR); \
;     __builtin_amdgcn_global_load_lds((const unsigned*)(_g + O0), (lds_u32*)((P) + swave * 1024), 16, 0, 0); \
;     __builtin_amdgcn_global_load_lds((const unsigned*)(_g + (size_t)64 * (LD) + O0), (lds_u32*)((P) + swave * 1024 + 8192), 16, 0, 0); } while (0)
; #define WAIT_V(n) asm volatile("s_waitcnt vmcnt(" #n ")" ::: "memory")
; #define BAR __builtin_amdgcn_s_barrier()
; __device__ __forceinline__ void gemm_stream(int swave, const GemmJob& J, char* shm, int vb, int G) {
;     ...
;   const int wid = tidx >> 6, lane = tidx & 63, wr = wid >> 2, wc = wid & 3, fr = lane & 15, fq = lane >> 4;
;   unsigned offA0, offA1, offB0;
;   { int _r, _c; stage_rc(tidx * 16, _r, _c); offA0 = _r * lda + _c; offA1 = _r * lda1 + _c; const int _rb = (_r & ~31) + perm32(_r & 31); offB0 = _rb * ldb + _c; }
;   const size_t hB = (size_t)128 * ldb;
;   int cg, cbrow, cbcol; const bf16_t* cA; const bf16_t* cA1; const bf16_t* cB;
;   auto decode = [&](int id, int& g, int& brow, int& bcol, const bf16_t*& pA, const bf16_t*& pA1, const bf16_t*& pB) {
;     int pm, pn; g = 0;
;     if (J.nb == 1) tile_map(id, J.nM, J.nN, pm, pn);
;     else { g = id / per; const int rem = id - g * per; pm = rem / J.nN; pn = rem - pm * J.nN; }
;     brow = pm * 256; bcol = pn * 256;
;     pA = J.A + (size_t)g * J.strideA + (size_t)brow * lda; pA1 = J.A1 + (size_t)g * J.strideA + (size_t)brow * lda1; pB = J.Bt + (size_t)g * J.strideB + (size_t)bcol * ldb;
;   };
;   int id = vb;
;   decode(id, cg, cbrow, cbcol, cA, cA1, cB);
;   f32x4 acc[2][2][4][2] = {};
;   bf16x8 At[4][2], B0[2][2], B1[2][2];
;   STG(SB(0, 0), cB, ldb, offB0); STGA(SA(0, 0), cA, cA1, 0, 0); STG(SB(0, 1), cB + hB, ldb, offB0); STGA(SA(0, 1), cA, cA1, 0, 1);
;   if (wr == 1) BAR;
;   WAIT_V(4); BAR;
;   STG(SB(1, 0), cB + 64, ldb, offB0); STGA(SA(1, 0), cA, cA1, 1, 0); STG(SB(1, 1), cB + hB + 64, ldb, offB0);
;   WAIT_V(6); BAR;
;   for (;;) {
;     const int nid = id + G; const bool has_next = nid < ntile;
;     int ng = cg, nbrow = cbrow, nbcol = cbcol; const bf16_t* nA = cA; const bf16_t* nA1 = cA1; const bf16_t* nB = cB;
;     if (has_next) decode(nid, ng, nbrow, nbcol, nA, nA1, nB);
.LBB0_725:
	s_or_b64 exec, exec, s[6:7]
	v_mad_u64_u32 v[138:139], s[6:7], v17, s37, v[2:3]
	s_mul_i32 s6, s10, s37
	s_mul_hi_u32 s7, s5, s37
	s_add_i32 s7, s7, s6
	s_mul_i32 s6, s5, s37
	s_lshr_b32 s49, s76, 6
	s_lshl_b64 s[6:7], s[6:7], 1
	v_readlane_b32 s10, v247, 55
	v_readlane_b32 s11, v247, 56
	s_add_u32 s16, s10, s6
	s_addc_u32 s17, s11, s7
	s_add_u32 s50, s10, 0xc000000
	v_readlane_b32 s7, v247, 28
	s_addc_u32 s51, s11, 0
	s_add_i32 s6, s7, s89
	v_lshl_add_u64 v[4:5], v[4:5], 0, s[22:23]
	s_mov_b32 m0, s6
	s_waitcnt vmcnt(4)
	s_barrier
	global_load_lds_dwordx4 v[4:5], off
	v_lshl_add_u64 v[4:5], v[6:7], 0, s[22:23]
	s_add_i32 m0, s6, 0x2000
	s_add_i32 s54, s42, 0x8000
	global_load_lds_dwordx4 v[4:5], off
	v_lshl_add_u64 v[4:5], v[8:9], 0, s[22:23]
	s_mov_b32 m0, s54
	s_add_i32 s55, s42, 0xa000
	v_readlane_b32 s10, v247, 29
	global_load_lds_dwordx4 v[4:5], off
	v_lshl_add_u64 v[4:5], v[10:11], 0, s[22:23]
	s_mov_b32 m0, s55
	s_add_i32 s6, s10, s89
	global_load_lds_dwordx4 v[4:5], off
	v_lshl_add_u64 v[4:5], v[12:13], 0, s[22:23]
	s_mov_b32 m0, s6
	v_and_b32_e32 v1, 15, v135
	global_load_lds_dwordx4 v[4:5], off
	v_lshl_add_u64 v[4:5], v[14:15], 0, s[22:23]
	s_add_i32 m0, s6, 0x2000
	v_bfe_u32 v19, v135, 4, 2
	global_load_lds_dwordx4 v[4:5], off
	v_lshlrev_b32_e32 v4, 2, v135
	v_lshlrev_b32_e32 v6, 4, v19
	v_lshlrev_b32_e32 v2, 6, v1
	v_and_b32_e32 v7, 32, v4
	v_bitop3_b32 v8, v6, v7, v2 bitop3:0x36
	s_add_i32 s6, 0, 0x10000
	v_add_u32_e32 v9, s6, v8
	s_add_i32 s6, 0, 0x14000
	v_add_u32_e32 v10, s6, v8
	v_lshlrev_b32_e32 v14, 6, v135
	s_movk_i32 s6, 0x3c0
	v_bfe_u32 v18, v135, 6, 2
	s_waitcnt vmcnt(6)
	v_lshlrev_b32_e32 v13, 13, v16
	v_and_or_b32 v6, v14, s6, v6
	v_lshlrev_b32_e32 v5, 12, v18
	v_add_u32_e32 v11, s7, v8
	v_add_u32_e32 v12, s10, v8
	v_lshlrev_b32_e32 v2, 5, v18
	v_lshlrev_b32_e32 v4, 3, v19
	v_add_u32_e32 v8, 0, v8
	v_xad_u32 v6, v6, v7, 0
	v_or_b32_e32 v7, 0x800, v13
	v_or_b32_e32 v14, 0x1000, v13
	v_or_b32_e32 v15, 0x1800, v13
	v_lshl_or_b32 v1, v16, 6, v1
	v_add_u32_e32 v139, v9, v5
	v_add_u32_e32 v144, v8, v13
	v_add_u32_e32 v145, v6, v7
	v_add_u32_e32 v159, v6, v14
	v_add_u32_e32 v160, v6, v15
	v_add_u32_e32 v161, v10, v5
	v_add_u32_e32 v162, v11, v5
	v_add_u32_e32 v163, v12, v5
	v_lshlrev_b32_e32 v140, 1, v2
	v_lshlrev_b32_e32 v142, 1, v4
	s_mov_b64 s[10:11], s[8:9]
	s_mov_b64 s[12:13], s[16:17]
	s_mov_b64 s[14:15], s[2:3]
	s_barrier
	v_readfirstlane_b32 s6, v135
	s_cmpk_lt_u32 s6, 0x100
	s_cbranch_scc1 .Lgemm_prio_skip
	s_setprio 1
.Lgemm_prio_skip:
.LBB0_726:
	s_add_i32 s19, s19, s67
	s_cmp_ge_i32 s19, s24
	s_cselect_b64 s[6:7], -1, 0
	s_and_b64 vcc, exec, s[6:7]
	s_mov_b32 s28, s5
	s_mov_b32 s56, s4
	s_cbranch_vccnz .LBB0_728
	s_ashr_i32 s10, s19, 31
	s_lshr_b32 s10, s10, 29
	s_add_i32 s10, s19, s10
	s_ashr_i32 s11, s10, 3
	s_and_b32 s10, s10, -8
	s_sub_i32 s10, s19, s10
	s_lshr_b32 s12, s10, 31
	s_or_b32 s12, s12, s25
	s_mul_i32 s10, s12, s10
	s_add_i32 s10, s10, s11
	s_abs_i32 s12, s10
	s_mul_hi_u32 s13, s12, s41
	s_mul_i32 s14, s13, s40
	s_ashr_i32 s11, s10, 31
	s_sub_i32 s12, s12, s14
	s_xor_b32 s11, s11, s35
	s_add_i32 s14, s13, 1
	s_sub_i32 s15, s12, s40
	s_cmp_ge_u32 s12, s40
	s_cselect_b32 s13, s14, s13
	s_cselect_b32 s12, s15, s12
	s_add_i32 s14, s13, 1
	s_cmp_ge_u32 s12, s40
	s_cselect_b32 s12, s14, s13
	s_xor_b32 s12, s12, s11
	s_sub_i32 s11, s12, s11
	s_lshl_b32 s12, s11, 3
	s_sub_i32 s13, 0x80, s12
	s_min_i32 s13, s13, 8
	s_abs_i32 s14, s13
	v_cvt_f32_u32_e32 v2, s14
	s_sub_i32 s20, 0, s14
	s_mul_i32 s11, s11, s34
	s_sub_i32 s10, s10, s11
	v_rcp_iflag_f32_e32 v2, v2
	s_abs_i32 s15, s10
	s_xor_b32 s11, s10, s13
	s_ashr_i32 s11, s11, 31
	v_mul_f32_e32 v2, 0x4f7ffffe, v2
	v_cvt_u32_f32_e32 v2, v2
	s_nop 0
	v_readfirstlane_b32 s21, v2
	s_mul_i32 s20, s20, s21
	s_mul_hi_u32 s20, s21, s20
	s_add_i32 s21, s21, s20
	s_mul_hi_u32 s20, s15, s21
	s_mul_i32 s21, s20, s14
	s_sub_i32 s15, s15, s21
	s_add_i32 s21, s20, 1
	s_sub_i32 s28, s15, s14
	s_cmp_ge_u32 s15, s14
	s_cselect_b32 s20, s21, s20
	s_cselect_b32 s15, s28, s15
	s_add_i32 s21, s20, 1
	s_cmp_ge_u32 s15, s14
	s_cselect_b32 s14, s21, s20
	s_xor_b32 s14, s14, s11
	s_sub_i32 s11, s14, s11
	s_mul_i32 s13, s11, s13
	s_sub_i32 s10, s10, s13
	s_add_i32 s10, s10, s12
	s_lshl_b32 s28, s10, 8
	s_ashr_i32 s12, s28, 31
	s_lshl_b32 s56, s11, 8
	s_mul_i32 s10, s12, s38
	s_mul_hi_u32 s11, s28, s38
	s_add_i32 s11, s11, s10
	s_mul_i32 s10, s28, s38
	s_lshl_b64 s[10:11], s[10:11], 1
	v_readlane_b32 s14, v246, 0
	v_readlane_b32 s15, v246, 1
	s_add_u32 s10, s14, s10
	s_mul_i32 s12, s12, s37
	s_mul_hi_u32 s13, s28, s37
	s_addc_u32 s11, s15, s11
	s_add_i32 s13, s13, s12
	s_mul_i32 s12, s28, s37
	s_lshl_b64 s[12:13], s[12:13], 1
	v_readlane_b32 s14, v247, 55
	v_readlane_b32 s15, v247, 56
	s_add_u32 s12, s14, s12
	s_addc_u32 s13, s15, s13
	s_ashr_i32 s14, s56, 31
	s_mul_i32 s14, s14, s76
	s_mul_hi_u32 s15, s56, s76
	s_add_i32 s15, s15, s14
	s_mul_i32 s14, s56, s76
	s_lshl_b64 s[14:15], s[14:15], 1
	v_readlane_b32 s20, v246, 2
	v_readlane_b32 s21, v246, 3
	s_add_u32 s14, s20, s14
	s_addc_u32 s15, s21, s15

; #define LDA(dst, b, h) for (int m = 0; m < 4; ++m) for (int k = 0; k < 2; ++k) \
;     dst[m][k] = *reinterpret_cast<const bf16x8*>(SA(b, h) + lds_byte(wr * 64 + m * 16 + fr, k * 32 + fq * 8))
; #define LDB(dst, b, h) for (int n = 0; n < 2; ++n) for (int k = 0; k < 2; ++k) \
;     dst[n][k] = *reinterpret_cast<const bf16x8*>(SB(b, h) + lds_byte(wc * 32 + n * 16 + fr, k * 32 + fq * 8))
; #define MMA(ai, bj, At_, Bt_) do { __builtin_amdgcn_s_setprio(1); \
;     for (int m = 0; m < 4; ++m) for (int n = 0; n < 2; ++n) for (int k = 0; k < 2; ++k) \
;       acc[ai][bj][m][n] = __builtin_amdgcn_mfma_f32_16x16x32_bf16(Bt_[n][k], At_[m][k], acc[ai][bj][m][n], 0, 0, 0); \
;     __builtin_amdgcn_s_setprio(0); } while (0)
; #define WAIT_V(n) asm volatile("s_waitcnt vmcnt(" #n ")" ::: "memory")
; #define WAIT_L(n) asm volatile("s_waitcnt lgkmcnt(" #n ")" ::: "memory")
; #define BAR __builtin_amdgcn_s_barrier()
; #define SCHED __builtin_amdgcn_sched_barrier(0)
; #define STG(P, PTR, LD, O0) do { const bf16_t* _g = (PTR); \
;     __builtin_amdgcn_global_load_lds((const unsigned*)(_g + O0), (lds_u32*)((P) + swave * 1024), 16, 0, 0); \
;     __builtin_amdgcn_global_load_lds((const unsigned*)(_g + (size_t)64 * (LD) + O0), (lds_u32*)((P) + swave * 1024 + 8192), 16, 0, 0); } while (0)
; #define LDA(dst, b, h) for (int m = 0; m < 4; ++m) for (int k = 0; k < 2; ++k) \
;     dst[m][k] = *reinterpret_cast<const bf16x8*>(SA(b, h) + lds_byte(wr * 64 + m * 16 + fr, k * 32 + fq * 8))
; #define LDB(dst, b, h) for (int n = 0; n < 2; ++n) for (int k = 0; k < 2; ++k) \
;     dst[n][k] = *reinterpret_cast<const bf16x8*>(SB(b, h) + lds_byte(wc * 32 + n * 16 + fr, k * 32 + fq * 8))
; #define WAIT_V(n) asm volatile("s_waitcnt vmcnt(" #n ")" ::: "memory")
; #define WAIT_L(n) asm volatile("s_waitcnt lgkmcnt(" #n ")" ::: "memory")
; __device__ __forceinline__ void gemm_stream(int swave, const GemmJob& J, char* shm, int vb, int G) {
;     ...
;       LDB(B0, 0, 0); SCHED; LDA(At, 0, 0); STGA(SA(1, 1), cA, cA1, t + 1, 1);
;       WAIT_L(8); BAR; WAIT_L(0); MMA(0, 0, At, B0); BAR; SCHED;
;       LDB(B1, 0, 1); STG(SB(0, 0), b2, ldb, offB0);
;       BAR; WAIT_L(0); MMA(0, 1, At, B1); BAR;
;       LDA(At, 0, 1); STGA(SA(0, 0), xA, xA1, k2, 0);
;       BAR; WAIT_L(0); MMA(1, 0, At, B0); BAR; SCHED;
;       STG(SB(0, 1), b2 + hB, ldb, offB0);
;       WAIT_V(6); BAR; MMA(1, 1, At, B1); BAR;
.LBB0_729:
	ds_read_b128 v[164:167], v139
	ds_read_b128 v[168:171], v139 offset:1024
	ds_read_b128 v[172:175], v139 offset:2048
	ds_read_b128 v[176:179], v139 offset:3072
	s_cmp_eq_u32 s49, s29
	s_cselect_b64 s[68:69], -1, 0
	s_and_b64 s[64:65], s[68:69], exec
	s_cselect_b32 s52, s10, s8
	s_cselect_b32 s64, s11, s9
	s_add_i32 s33, s2, 2
	s_and_b64 s[68:69], s[68:69], exec
	s_cselect_b32 s71, s15, s21
	s_cselect_b32 s70, s14, s20
	s_cselect_b32 s68, 0, s33
	s_cselect_b32 s65, s12, s16
	s_cselect_b32 s66, s13, s17
	s_or_b32 s2, s2, 1
	s_cmp_lt_u32 s2, s36
	s_cselect_b64 vcc, -1, 0
	s_and_b64 s[2:3], vcc, exec
	s_cselect_b32 s3, 0, s36
	s_cselect_b32 s2, s38, s37
	s_not_b32 s3, s3
	s_add_i32 s94, s3, s29
	s_and_b64 s[72:73], vcc, exec
	s_cselect_b32 s3, s9, s17
	s_cselect_b32 s69, s8, s16
	s_lshl_b64 s[72:73], s[94:95], 7
	s_add_u32 s69, s69, s72
	s_addc_u32 s74, s3, s73
	s_mov_b32 s3, s95
	s_lshl_b64 s[72:73], s[2:3], 8
	s_add_u32 s72, s69, s72
	v_cndmask_b32_e32 v2, v138, v0, vcc
	s_addc_u32 s73, s74, s73
	s_add_i32 m0, s42, 0xc000
	s_lshl_b64 s[2:3], s[2:3], 7
	v_lshlrev_b64 v[212:213], 1, v[2:3]
	s_add_u32 s2, s72, s2
	v_lshl_add_u64 v[214:215], s[72:73], 0, v[212:213]
	s_addc_u32 s3, s73, s3
	ds_read_b128 v[180:183], v144
	ds_read_b128 v[184:187], v144 offset:1024
	ds_read_b128 v[188:191], v145
	ds_read_b128 v[192:195], v145 offset:1024
	ds_read_b128 v[196:199], v159
	ds_read_b128 v[200:203], v159 offset:1024
	ds_read_b128 v[204:207], v160
	ds_read_b128 v[208:211], v160 offset:1024
	global_load_lds_dwordx4 v[214:215], off
	v_lshl_add_u64 v[212:213], s[2:3], 0, v[212:213]
	s_add_i32 m0, s42, 0xe000
	s_nop 0
	global_load_lds_dwordx4 v[212:213], off
	s_waitcnt lgkmcnt(8)
	s_barrier
	s_waitcnt lgkmcnt(0)
	s_waitcnt lgkmcnt(0)
	v_mfma_f32_16x16x32_bf16 v[128:131], v[164:167], v[180:183], v[128:131]
	v_mfma_f32_16x16x32_bf16 v[124:127], v[172:175], v[180:183], v[124:127]
	v_mfma_f32_16x16x32_bf16 v[120:123], v[164:167], v[188:191], v[120:123]
	v_mfma_f32_16x16x32_bf16 v[116:119], v[172:175], v[188:191], v[116:119]
	v_mfma_f32_16x16x32_bf16 v[104:107], v[164:167], v[196:199], v[104:107]
	v_mfma_f32_16x16x32_bf16 v[100:103], v[172:175], v[196:199], v[100:103]
	v_mfma_f32_16x16x32_bf16 v[88:91], v[164:167], v[204:207], v[88:91]
	v_mfma_f32_16x16x32_bf16 v[84:87], v[172:175], v[204:207], v[84:87]
	v_mfma_f32_16x16x32_bf16 v[128:131], v[168:171], v[184:187], v[128:131]
	v_mfma_f32_16x16x32_bf16 v[124:127], v[176:179], v[184:187], v[124:127]
	v_mfma_f32_16x16x32_bf16 v[120:123], v[168:171], v[192:195], v[120:123]
	v_mfma_f32_16x16x32_bf16 v[116:119], v[176:179], v[192:195], v[116:119]
	v_mfma_f32_16x16x32_bf16 v[104:107], v[168:171], v[200:203], v[104:107]
	v_mfma_f32_16x16x32_bf16 v[100:103], v[176:179], v[200:203], v[100:103]
	v_mfma_f32_16x16x32_bf16 v[88:91], v[168:171], v[208:211], v[88:91]
	v_mfma_f32_16x16x32_bf16 v[84:87], v[176:179], v[208:211], v[84:87]
	s_barrier
	s_add_u32 s2, s70, s0
	s_mov_b32 m0, s43
	v_lshl_add_u64 v[228:229], s[70:71], 0, v[136:137]
	s_addc_u32 s3, s71, s1
	ds_read_b128 v[212:215], v161
	ds_read_b128 v[216:219], v161 offset:1024
	ds_read_b128 v[220:223], v161 offset:2048
	ds_read_b128 v[224:227], v161 offset:3072
	global_load_lds_dwordx4 v[228:229], off
	v_lshl_add_u64 v[230:231], s[2:3], 0, v[136:137]
	s_mov_b32 m0, s44
	s_nop 0
	global_load_lds_dwordx4 v[230:231], off
	s_barrier
	s_waitcnt lgkmcnt(0)
	s_waitcnt lgkmcnt(0)
	v_mfma_f32_16x16x32_bf16 v[112:115], v[212:215], v[180:183], v[112:115]
	v_mfma_f32_16x16x32_bf16 v[108:111], v[220:223], v[180:183], v[108:111]
	v_mfma_f32_16x16x32_bf16 v[96:99], v[212:215], v[188:191], v[96:99]
	v_mfma_f32_16x16x32_bf16 v[92:95], v[220:223], v[188:191], v[92:95]
	v_mfma_f32_16x16x32_bf16 v[80:83], v[212:215], v[196:199], v[80:83]
	v_mfma_f32_16x16x32_bf16 v[76:79], v[220:223], v[196:199], v[76:79]
	v_mfma_f32_16x16x32_bf16 v[72:75], v[212:215], v[204:207], v[72:75]
	v_mfma_f32_16x16x32_bf16 v[68:71], v[220:223], v[204:207], v[68:71]
	v_mfma_f32_16x16x32_bf16 v[112:115], v[216:219], v[184:187], v[112:115]
	v_mfma_f32_16x16x32_bf16 v[108:111], v[224:227], v[184:187], v[108:111]
	v_mfma_f32_16x16x32_bf16 v[96:99], v[216:219], v[192:195], v[96:99]
	v_mfma_f32_16x16x32_bf16 v[92:95], v[224:227], v[192:195], v[92:95]
	v_mfma_f32_16x16x32_bf16 v[80:83], v[216:219], v[200:203], v[80:83]
	v_mfma_f32_16x16x32_bf16 v[76:79], v[224:227], v[200:203], v[76:79]
	v_mfma_f32_16x16x32_bf16 v[72:75], v[216:219], v[208:211], v[72:75]
	v_mfma_f32_16x16x32_bf16 v[68:71], v[224:227], v[208:211], v[68:71]
	s_cmp_lt_u32 s68, s36
	s_cselect_b64 vcc, -1, 0
	s_and_b64 s[70:71], vcc, exec
	s_cselect_b32 s70, s38, s37
	s_sub_i32 s69, s68, s36
	s_min_u32 s94, s68, s69
	s_and_b64 s[72:73], vcc, exec
	s_cselect_b32 s69, s64, s66
	s_cselect_b32 s71, s52, s65
	s_lshl_b64 s[72:73], s[94:95], 7
	v_cndmask_b32_e32 v2, v138, v0, vcc
	s_add_u32 s72, s71, s72
	s_mov_b32 s71, s95
	s_addc_u32 s73, s69, s73
	v_lshlrev_b64 v[232:233], 1, v[2:3]
	s_lshl_b64 s[70:71], s[70:71], 7
	v_lshl_add_u64 v[234:235], s[72:73], 0, v[232:233]
	s_add_u32 s72, s72, s70
	s_mov_b32 m0, s42
	s_addc_u32 s73, s73, s71
	s_barrier
	ds_read_b128 v[180:183], v144 offset:16384
	ds_read_b128 v[184:187], v144 offset:17408
	ds_read_b128 v[188:191], v145 offset:16384
	ds_read_b128 v[192:195], v145 offset:17408
	ds_read_b128 v[196:199], v159 offset:16384
	ds_read_b128 v[200:203], v159 offset:17408
	ds_read_b128 v[204:207], v160 offset:16384
	ds_read_b128 v[208:211], v160 offset:17408
	global_load_lds_dwordx4 v[234:235], off
	v_lshl_add_u64 v[234:235], s[72:73], 0, v[232:233]
	s_mov_b32 m0, s39
	s_nop 0
	global_load_lds_dwordx4 v[234:235], off
	s_barrier
; #define LDA(dst, b, h) for (int m = 0; m < 4; ++m) for (int k = 0; k < 2; ++k) \
;     dst[m][k] = *reinterpret_cast<const bf16x8*>(SA(b, h) + lds_byte(wr * 64 + m * 16 + fr, k * 32 + fq * 8))
; #define LDB(dst, b, h) for (int n = 0; n < 2; ++n) for (int k = 0; k < 2; ++k) \
;     dst[n][k] = *reinterpret_cast<const bf16x8*>(SB(b, h) + lds_byte(wc * 32 + n * 16 + fr, k * 32 + fq * 8))
; #define MMA(ai, bj, At_, Bt_) do { __builtin_amdgcn_s_setprio(1); \
;     for (int m = 0; m < 4; ++m) for (int n = 0; n < 2; ++n) for (int k = 0; k < 2; ++k) \
;       acc[ai][bj][m][n] = __builtin_amdgcn_mfma_f32_16x16x32_bf16(Bt_[n][k], At_[m][k], acc[ai][bj][m][n], 0, 0, 0); \
;     __builtin_amdgcn_s_setprio(0); } while (0)
; #define WAIT_V(n) asm volatile("s_waitcnt vmcnt(" #n ")" ::: "memory")
; #define WAIT_L(n) asm volatile("s_waitcnt lgkmcnt(" #n ")" ::: "memory")
; #define BAR __builtin_amdgcn_s_barrier()
; #define SCHED __builtin_amdgcn_sched_barrier(0)
; #define STG(P, PTR, LD, O0) do { const bf16_t* _g = (PTR); \
;     __builtin_amdgcn_global_load_lds((const unsigned*)(_g + O0), (lds_u32*)((P) + swave * 1024), 16, 0, 0); \
;     __builtin_amdgcn_global_load_lds((const unsigned*)(_g + (size_t)64 * (LD) + O0), (lds_u32*)((P) + swave * 1024 + 8192), 16, 0, 0); } while (0)
; #define LDA(dst, b, h) for (int m = 0; m < 4; ++m) for (int k = 0; k < 2; ++k) \
;     dst[m][k] = *reinterpret_cast<const bf16x8*>(SA(b, h) + lds_byte(wr * 64 + m * 16 + fr, k * 32 + fq * 8))
; #define LDB(dst, b, h) for (int n = 0; n < 2; ++n) for (int k = 0; k < 2; ++k) \
;     dst[n][k] = *reinterpret_cast<const bf16x8*>(SB(b, h) + lds_byte(wc * 32 + n * 16 + fr, k * 32 + fq * 8))
; #define WAIT_V(n) asm volatile("s_waitcnt vmcnt(" #n ")" ::: "memory")
; #define WAIT_L(n) asm volatile("s_waitcnt lgkmcnt(" #n ")" ::: "memory")
; #define BAR __builtin_amdgcn_s_barrier()
; __device__ __forceinline__ void gemm_stream(int swave, const GemmJob& J, char* shm, int vb, int G) {
;     ...
;       WAIT_V(6); BAR; MMA(1, 1, At, B1); BAR;
;       LDB(B0, 1, 0); SCHED; LDA(At, 1, 0); STGA(SA(0, 1), xA, xA1, k2, 1);
;       WAIT_L(8); BAR; WAIT_L(0); MMA(0, 0, At, B0); BAR; SCHED;
;       LDB(B1, 1, 1); STG(SB(1, 0), b3, ldb, offB0);
;       BAR; WAIT_L(0); MMA(0, 1, At, B1); BAR;
;       LDA(At, 1, 1); STGA(SA(1, 0), xA, xA1, k2 + 1, 0);
;       BAR; WAIT_L(0); MMA(1, 0, At, B0); BAR; SCHED;
	s_waitcnt lgkmcnt(0)
	s_waitcnt lgkmcnt(0)
	v_mfma_f32_16x16x32_bf16 v[64:67], v[164:167], v[180:183], v[64:67]
	v_mfma_f32_16x16x32_bf16 v[60:63], v[172:175], v[180:183], v[60:63]
	v_mfma_f32_16x16x32_bf16 v[56:59], v[164:167], v[188:191], v[56:59]
	v_mfma_f32_16x16x32_bf16 v[52:55], v[172:175], v[188:191], v[52:55]
	v_mfma_f32_16x16x32_bf16 v[40:43], v[164:167], v[196:199], v[40:43]
	v_mfma_f32_16x16x32_bf16 v[36:39], v[172:175], v[196:199], v[36:39]
	v_mfma_f32_16x16x32_bf16 v[24:27], v[164:167], v[204:207], v[24:27]
	v_mfma_f32_16x16x32_bf16 v[20:23], v[172:175], v[204:207], v[20:23]
	v_mfma_f32_16x16x32_bf16 v[64:67], v[168:171], v[184:187], v[64:67]
	v_mfma_f32_16x16x32_bf16 v[60:63], v[176:179], v[184:187], v[60:63]
	v_mfma_f32_16x16x32_bf16 v[56:59], v[168:171], v[192:195], v[56:59]
	v_mfma_f32_16x16x32_bf16 v[52:55], v[176:179], v[192:195], v[52:55]
	v_mfma_f32_16x16x32_bf16 v[40:43], v[168:171], v[200:203], v[40:43]
	v_mfma_f32_16x16x32_bf16 v[36:39], v[176:179], v[200:203], v[36:39]
	v_mfma_f32_16x16x32_bf16 v[24:27], v[168:171], v[208:211], v[24:27]
	v_mfma_f32_16x16x32_bf16 v[20:23], v[176:179], v[208:211], v[20:23]
	s_barrier
	s_add_u32 s2, s2, s0
	s_addc_u32 s3, s3, s1
	v_lshl_add_u64 v[234:235], s[2:3], 0, v[136:137]
	s_add_u32 s2, s2, s0
	s_mov_b32 m0, s45
	s_addc_u32 s3, s3, s1
	global_load_lds_dwordx4 v[234:235], off
	v_lshl_add_u64 v[236:237], s[2:3], 0, v[136:137]
	s_mov_b32 m0, s46
	s_nop 0
	global_load_lds_dwordx4 v[236:237], off
	s_waitcnt vmcnt(6)
	s_barrier
	v_mfma_f32_16x16x32_bf16 v[48:51], v[212:215], v[180:183], v[48:51]
	v_mfma_f32_16x16x32_bf16 v[44:47], v[220:223], v[180:183], v[44:47]
	v_mfma_f32_16x16x32_bf16 v[32:35], v[212:215], v[188:191], v[32:35]
	v_mfma_f32_16x16x32_bf16 v[28:31], v[220:223], v[188:191], v[28:31]
	v_mfma_f32_16x16x32_bf16 v[16:19], v[212:215], v[196:199], v[16:19]
	v_mfma_f32_16x16x32_bf16 v[12:15], v[220:223], v[196:199], v[12:15]
	v_mfma_f32_16x16x32_bf16 v[8:11], v[212:215], v[204:207], v[8:11]
	v_mfma_f32_16x16x32_bf16 v[4:7], v[220:223], v[204:207], v[4:7]
	v_mfma_f32_16x16x32_bf16 v[48:51], v[216:219], v[184:187], v[48:51]
	v_mfma_f32_16x16x32_bf16 v[44:47], v[224:227], v[184:187], v[44:47]
	v_mfma_f32_16x16x32_bf16 v[32:35], v[216:219], v[192:195], v[32:35]
	v_mfma_f32_16x16x32_bf16 v[28:31], v[224:227], v[192:195], v[28:31]
	v_mfma_f32_16x16x32_bf16 v[16:19], v[216:219], v[200:203], v[16:19]
	v_mfma_f32_16x16x32_bf16 v[12:15], v[224:227], v[200:203], v[12:15]
	v_mfma_f32_16x16x32_bf16 v[8:11], v[216:219], v[208:211], v[8:11]
	v_mfma_f32_16x16x32_bf16 v[4:7], v[224:227], v[208:211], v[4:7]
	s_barrier
	ds_read_b128 v[164:167], v162
	ds_read_b128 v[168:171], v162 offset:1024
	ds_read_b128 v[172:175], v162 offset:2048
	ds_read_b128 v[176:179], v162 offset:3072
	s_add_u32 s2, s72, s70
	s_addc_u32 s3, s73, s71
	v_lshl_add_u64 v[212:213], s[2:3], 0, v[232:233]
	s_add_u32 s2, s2, s70
	s_mov_b32 m0, s47
	s_addc_u32 s3, s3, s71
	ds_read_b128 v[180:183], v144 offset:32768
	ds_read_b128 v[184:187], v144 offset:33792
	ds_read_b128 v[188:191], v145 offset:32768
	ds_read_b128 v[192:195], v145 offset:33792
	ds_read_b128 v[196:199], v159 offset:32768
	ds_read_b128 v[200:203], v159 offset:33792
	ds_read_b128 v[204:207], v160 offset:32768
	ds_read_b128 v[208:211], v160 offset:33792
	global_load_lds_dwordx4 v[212:213], off
	v_lshl_add_u64 v[212:213], s[2:3], 0, v[232:233]
	s_mov_b32 m0, s48
	s_nop 0
	global_load_lds_dwordx4 v[212:213], off
	s_waitcnt lgkmcnt(8)
	s_barrier
	s_waitcnt lgkmcnt(0)
	s_waitcnt lgkmcnt(0)
	v_mfma_f32_16x16x32_bf16 v[128:131], v[164:167], v[180:183], v[128:131]
	v_mfma_f32_16x16x32_bf16 v[124:127], v[172:175], v[180:183], v[124:127]
	v_mfma_f32_16x16x32_bf16 v[120:123], v[164:167], v[188:191], v[120:123]
	v_mfma_f32_16x16x32_bf16 v[116:119], v[172:175], v[188:191], v[116:119]
	v_mfma_f32_16x16x32_bf16 v[104:107], v[164:167], v[196:199], v[104:107]
	v_mfma_f32_16x16x32_bf16 v[100:103], v[172:175], v[196:199], v[100:103]
	v_mfma_f32_16x16x32_bf16 v[88:91], v[164:167], v[204:207], v[88:91]
	v_mfma_f32_16x16x32_bf16 v[84:87], v[172:175], v[204:207], v[84:87]
	v_mfma_f32_16x16x32_bf16 v[128:131], v[168:171], v[184:187], v[128:131]
	v_mfma_f32_16x16x32_bf16 v[124:127], v[176:179], v[184:187], v[124:127]
	v_mfma_f32_16x16x32_bf16 v[120:123], v[168:171], v[192:195], v[120:123]
	v_mfma_f32_16x16x32_bf16 v[116:119], v[176:179], v[192:195], v[116:119]
	v_mfma_f32_16x16x32_bf16 v[104:107], v[168:171], v[200:203], v[104:107]
	v_mfma_f32_16x16x32_bf16 v[100:103], v[176:179], v[200:203], v[100:103]
	v_mfma_f32_16x16x32_bf16 v[88:91], v[168:171], v[208:211], v[88:91]
	v_mfma_f32_16x16x32_bf16 v[84:87], v[176:179], v[208:211], v[84:87]
	s_barrier
	v_lshl_add_u64 v[228:229], v[228:229], 0, s[22:23]
	s_add_i32 m0, s42, 0x18000
	ds_read_b128 v[212:215], v163
	ds_read_b128 v[216:219], v163 offset:1024
	ds_read_b128 v[220:223], v163 offset:2048
	ds_read_b128 v[224:227], v163 offset:3072
	global_load_lds_dwordx4 v[228:229], off
	v_lshl_add_u64 v[228:229], v[230:231], 0, s[22:23]
	s_add_i32 m0, s42, 0x1a000
	s_nop 0
	global_load_lds_dwordx4 v[228:229], off
	s_barrier
; #define LDA(dst, b, h) for (int m = 0; m < 4; ++m) for (int k = 0; k < 2; ++k) \
;     dst[m][k] = *reinterpret_cast<const bf16x8*>(SA(b, h) + lds_byte(wr * 64 + m * 16 + fr, k * 32 + fq * 8))
; #define MMA(ai, bj, At_, Bt_) do { __builtin_amdgcn_s_setprio(1); \
;     for (int m = 0; m < 4; ++m) for (int n = 0; n < 2; ++n) for (int k = 0; k < 2; ++k) \
;       acc[ai][bj][m][n] = __builtin_amdgcn_mfma_f32_16x16x32_bf16(Bt_[n][k], At_[m][k], acc[ai][bj][m][n], 0, 0, 0); \
;     __builtin_amdgcn_s_setprio(0); } while (0)
; #define WAIT_V(n) asm volatile("s_waitcnt vmcnt(" #n ")" ::: "memory")
; #define WAIT_L(n) asm volatile("s_waitcnt lgkmcnt(" #n ")" ::: "memory")
; #define BAR __builtin_amdgcn_s_barrier()
; #define SCHED __builtin_amdgcn_sched_barrier(0)
; #define STG(P, PTR, LD, O0) do { const bf16_t* _g = (PTR); \
;     __builtin_amdgcn_global_load_lds((const unsigned*)(_g + O0), (lds_u32*)((P) + swave * 1024), 16, 0, 0); \
;     __builtin_amdgcn_global_load_lds((const unsigned*)(_g + (size_t)64 * (LD) + O0), (lds_u32*)((P) + swave * 1024 + 8192), 16, 0, 0); } while (0)
; #define LDA(dst, b, h) for (int m = 0; m < 4; ++m) for (int k = 0; k < 2; ++k) \
;     dst[m][k] = *reinterpret_cast<const bf16x8*>(SA(b, h) + lds_byte(wr * 64 + m * 16 + fr, k * 32 + fq * 8))
; #define MMA(ai, bj, At_, Bt_) do { __builtin_amdgcn_s_setprio(1); \
;     for (int m = 0; m < 4; ++m) for (int n = 0; n < 2; ++n) for (int k = 0; k < 2; ++k) \
;       acc[ai][bj][m][n] = __builtin_amdgcn_mfma_f32_16x16x32_bf16(Bt_[n][k], At_[m][k], acc[ai][bj][m][n], 0, 0, 0); \
;     __builtin_amdgcn_s_setprio(0); } while (0)
; #define WAIT_V(n) asm volatile("s_waitcnt vmcnt(" #n ")" ::: "memory")
; #define WAIT_L(n) asm volatile("s_waitcnt lgkmcnt(" #n ")" ::: "memory")
; #define BAR __builtin_amdgcn_s_barrier()
; #define SCHED __builtin_amdgcn_sched_barrier(0)
; __device__ __forceinline__ void gemm_stream(int swave, const GemmJob& J, char* shm, int vb, int G) {
;     ...
;       LDA(At, 1, 1); STGA(SA(1, 0), xA, xA1, k2 + 1, 0);
;       BAR; WAIT_L(0); MMA(1, 0, At, B0); BAR; SCHED;
;       STG(SB(1, 1), b3 + hB, ldb, offB0);
;       WAIT_V(6); BAR; MMA(1, 1, At, B1); BAR;
;     }
	s_waitcnt lgkmcnt(0)
	s_waitcnt lgkmcnt(0)
	v_mfma_f32_16x16x32_bf16 v[112:115], v[212:215], v[180:183], v[112:115]
	v_mfma_f32_16x16x32_bf16 v[108:111], v[220:223], v[180:183], v[108:111]
	v_mfma_f32_16x16x32_bf16 v[96:99], v[212:215], v[188:191], v[96:99]
	v_mfma_f32_16x16x32_bf16 v[92:95], v[220:223], v[188:191], v[92:95]
	v_mfma_f32_16x16x32_bf16 v[80:83], v[212:215], v[196:199], v[80:83]
	v_mfma_f32_16x16x32_bf16 v[76:79], v[220:223], v[196:199], v[76:79]
	v_mfma_f32_16x16x32_bf16 v[72:75], v[212:215], v[204:207], v[72:75]
	v_mfma_f32_16x16x32_bf16 v[68:71], v[220:223], v[204:207], v[68:71]
	v_mfma_f32_16x16x32_bf16 v[112:115], v[216:219], v[184:187], v[112:115]
	v_mfma_f32_16x16x32_bf16 v[108:111], v[224:227], v[184:187], v[108:111]
	v_mfma_f32_16x16x32_bf16 v[96:99], v[216:219], v[192:195], v[96:99]
	v_mfma_f32_16x16x32_bf16 v[92:95], v[224:227], v[192:195], v[92:95]
	v_mfma_f32_16x16x32_bf16 v[80:83], v[216:219], v[200:203], v[80:83]
	v_mfma_f32_16x16x32_bf16 v[76:79], v[224:227], v[200:203], v[76:79]
	v_mfma_f32_16x16x32_bf16 v[72:75], v[216:219], v[208:211], v[72:75]
	v_mfma_f32_16x16x32_bf16 v[68:71], v[224:227], v[208:211], v[68:71]
	s_or_b32 s68, s68, 1
	s_cmp_lt_u32 s68, s36
	s_cselect_b64 vcc, -1, 0
	s_and_b64 s[2:3], vcc, exec
	s_cselect_b32 s69, s38, s37
	s_sub_i32 s2, s68, s36
	s_min_u32 s94, s68, s2
	s_and_b64 s[2:3], vcc, exec
	s_cselect_b32 s64, s64, s66
	s_cselect_b32 s52, s52, s65
	s_lshl_b64 s[2:3], s[94:95], 7
	v_cndmask_b32_e32 v2, v138, v0, vcc
	s_add_u32 s2, s52, s2
	s_addc_u32 s3, s64, s3
	v_lshlrev_b64 v[228:229], 1, v[2:3]
	s_lshl_b32 s52, s69, 7
	v_lshl_add_u64 v[230:231], s[2:3], 0, v[228:229]
	s_add_u32 s2, s2, s52
	s_mov_b32 m0, s54
	s_addc_u32 s3, s3, 0
	s_barrier
	ds_read_b128 v[180:183], v144 offset:49152
	ds_read_b128 v[184:187], v144 offset:50176
	ds_read_b128 v[188:191], v145 offset:49152
	ds_read_b128 v[192:195], v145 offset:50176
	ds_read_b128 v[196:199], v159 offset:49152
	ds_read_b128 v[200:203], v159 offset:50176
	ds_read_b128 v[204:207], v160 offset:49152
	ds_read_b128 v[208:211], v160 offset:50176
	global_load_lds_dwordx4 v[230:231], off
	v_lshl_add_u64 v[228:229], s[2:3], 0, v[228:229]
	s_mov_b32 m0, s55
	s_nop 0
	global_load_lds_dwordx4 v[228:229], off
	s_barrier
	s_waitcnt lgkmcnt(0)
	s_waitcnt lgkmcnt(0)
	v_mfma_f32_16x16x32_bf16 v[64:67], v[164:167], v[180:183], v[64:67]
	v_mfma_f32_16x16x32_bf16 v[60:63], v[172:175], v[180:183], v[60:63]
	v_mfma_f32_16x16x32_bf16 v[56:59], v[164:167], v[188:191], v[56:59]
	v_mfma_f32_16x16x32_bf16 v[52:55], v[172:175], v[188:191], v[52:55]
	v_mfma_f32_16x16x32_bf16 v[40:43], v[164:167], v[196:199], v[40:43]
	v_mfma_f32_16x16x32_bf16 v[36:39], v[172:175], v[196:199], v[36:39]
	v_mfma_f32_16x16x32_bf16 v[24:27], v[164:167], v[204:207], v[24:27]
	v_mfma_f32_16x16x32_bf16 v[20:23], v[172:175], v[204:207], v[20:23]
	v_mfma_f32_16x16x32_bf16 v[64:67], v[168:171], v[184:187], v[64:67]
	v_mfma_f32_16x16x32_bf16 v[60:63], v[176:179], v[184:187], v[60:63]
	v_mfma_f32_16x16x32_bf16 v[56:59], v[168:171], v[192:195], v[56:59]
	v_mfma_f32_16x16x32_bf16 v[52:55], v[176:179], v[192:195], v[52:55]
	v_mfma_f32_16x16x32_bf16 v[40:43], v[168:171], v[200:203], v[40:43]
	v_mfma_f32_16x16x32_bf16 v[36:39], v[176:179], v[200:203], v[36:39]
	v_mfma_f32_16x16x32_bf16 v[24:27], v[168:171], v[208:211], v[24:27]
	v_mfma_f32_16x16x32_bf16 v[20:23], v[176:179], v[208:211], v[20:23]
	s_barrier
	v_lshl_add_u64 v[164:165], v[234:235], 0, s[22:23]
	s_add_i32 m0, s42, 0x1c000
	s_nop 0
	global_load_lds_dwordx4 v[164:165], off
	v_lshl_add_u64 v[164:165], v[236:237], 0, s[22:23]
	s_add_i32 m0, s42, 0x1e000
	s_nop 0
	global_load_lds_dwordx4 v[164:165], off
	s_waitcnt vmcnt(6)
	s_barrier
	v_mfma_f32_16x16x32_bf16 v[48:51], v[212:215], v[180:183], v[48:51]
	v_mfma_f32_16x16x32_bf16 v[44:47], v[220:223], v[180:183], v[44:47]
	v_mfma_f32_16x16x32_bf16 v[32:35], v[212:215], v[188:191], v[32:35]
	v_mfma_f32_16x16x32_bf16 v[28:31], v[220:223], v[188:191], v[28:31]
	v_mfma_f32_16x16x32_bf16 v[16:19], v[212:215], v[196:199], v[16:19]
	v_mfma_f32_16x16x32_bf16 v[12:15], v[220:223], v[196:199], v[12:15]
	v_mfma_f32_16x16x32_bf16 v[8:11], v[212:215], v[204:207], v[8:11]
	v_mfma_f32_16x16x32_bf16 v[4:7], v[220:223], v[204:207], v[4:7]
	v_mfma_f32_16x16x32_bf16 v[48:51], v[216:219], v[184:187], v[48:51]
	v_mfma_f32_16x16x32_bf16 v[44:47], v[224:227], v[184:187], v[44:47]
	v_mfma_f32_16x16x32_bf16 v[32:35], v[216:219], v[192:195], v[32:35]
	v_mfma_f32_16x16x32_bf16 v[28:31], v[224:227], v[192:195], v[28:31]
	v_mfma_f32_16x16x32_bf16 v[16:19], v[216:219], v[200:203], v[16:19]
	v_mfma_f32_16x16x32_bf16 v[12:15], v[224:227], v[200:203], v[12:15]
	v_mfma_f32_16x16x32_bf16 v[8:11], v[216:219], v[208:211], v[8:11]
	v_mfma_f32_16x16x32_bf16 v[4:7], v[224:227], v[208:211], v[4:7]
	s_add_i32 s29, s29, 2
	s_add_u32 s20, s20, 0x100
	s_addc_u32 s21, s21, 0
	s_cmp_ge_u32 s33, s49
	s_mov_b32 s2, s33
	s_barrier
	s_cbranch_scc0 .LBB0_729
; __device__ __forceinline__ unsigned pk2(float lo, float hi) { f32x2_t v = {lo, hi}; bf16x2_t b = __builtin_convertvector(v, bf16x2_t); return __builtin_bit_cast(unsigned, b); }
; #define WAIT_V(n) asm volatile("s_waitcnt vmcnt(" #n ")" ::: "memory")
; #define BAR __builtin_amdgcn_s_barrier()
; #define WAIT_V(n) asm volatile("s_waitcnt vmcnt(" #n ")" ::: "memory")
; #define BAR __builtin_amdgcn_s_barrier()
; __device__ __forceinline__ void gemm_stream(int swave, const GemmJob& J, char* shm, int vb, int G) {
;     ...
;     {
;       bf16_t* C = (bf16_t*)((char*)J.c0 + (size_t)cg * J.strideC);
; #pragma unroll
;       for (int ai = 0; ai < 2; ++ai)
; #pragma unroll
;         for (int m = 0; m < 4; ++m)
; #pragma unroll
;           for (int bj = 0; bj < 2; ++bj) {
;             const f32x4 v0 = acc[ai][bj][m][0], v1 = acc[ai][bj][m][1];
;             uint4 o; o.x = pk2(v0[0], v0[1]); o.y = pk2(v0[2], v0[3]); o.z = pk2(v1[0], v1[1]); o.w = pk2(v1[2], v1[3]);
;             *(uint4*)(C + (size_t)(cbrow + ai * 128 + wr * 64 + m * 16 + fr) * J.ldc + cbcol + bj * 128 + wc * 32 + fq * 8) = o;
;           }
;     }
;     if (!has_next) break;
; #pragma unroll
;     for (int a_ = 0; a_ < 2; ++a_)
; #pragma unroll
;       for (int b_ = 0; b_ < 2; ++b_)
; #pragma unroll
;         for (int m = 0; m < 4; ++m)
; #pragma unroll
;           for (int n = 0; n < 2; ++n) acc[a_][b_][m][n] = (f32x4){0.f, 0.f, 0.f, 0.f};
;     id = nid; cg = ng; cbrow = nbrow; cbcol = nbcol; cA = nA; cA1 = nA1; cB = nB;
;   }
;   WAIT_V(0);
;   if (wr == 0) BAR;
	v_add_u32_e32 v164, s5, v1
	s_ashr_i32 s5, s4, 31
	s_lshl_b64 s[2:3], s[4:5], 1
	v_ashrrev_i32_e32 v2, 31, v164
	s_add_u32 s2, s50, s2
	v_cvt_pk_bf16_f32 v128, v128, v129
	v_cvt_pk_bf16_f32 v129, v130, v131
	v_cvt_pk_bf16_f32 v130, v124, v125
	v_mul_lo_u32 v2, v2, s18
	v_mad_u64_u32 v[124:125], s[4:5], v164, s18, 0
	s_addc_u32 s3, s51, s3
	v_add_u32_e32 v125, v125, v2
	v_lshl_add_u64 v[124:125], v[124:125], 1, s[2:3]
	v_mov_b32_e32 v141, v3
	v_lshl_add_u64 v[124:125], v[124:125], 0, v[140:141]
	v_mov_b32_e32 v143, v3
	v_lshl_add_u64 v[124:125], v[124:125], 0, v[142:143]
	v_cvt_pk_bf16_f32 v112, v112, v113
	v_cvt_pk_bf16_f32 v113, v114, v115
	v_cvt_pk_bf16_f32 v114, v108, v109
	v_cvt_pk_bf16_f32 v115, v110, v111
	global_store_dwordx4 v[124:125], v[112:115], off offset:256
	v_cvt_pk_bf16_f32 v131, v126, v127
	v_cvt_pk_bf16_f32 v96, v96, v97
	v_or_b32_e32 v112, 16, v164
	v_mad_u64_u32 v[112:113], s[4:5], v112, s18, 0
	v_add_u32_e32 v113, v113, v2
	v_lshl_add_u64 v[112:113], v[112:113], 1, s[2:3]
	v_lshl_add_u64 v[112:113], v[112:113], 0, v[140:141]
	v_lshl_add_u64 v[112:113], v[112:113], 0, v[142:143]
	v_cvt_pk_bf16_f32 v97, v98, v99
	v_cvt_pk_bf16_f32 v98, v92, v93
	v_cvt_pk_bf16_f32 v99, v94, v95
	global_store_dwordx4 v[124:125], v[128:131], off
	global_store_dwordx4 v[112:113], v[96:99], off offset:256
	v_cvt_pk_bf16_f32 v108, v120, v121
	v_cvt_pk_bf16_f32 v109, v122, v123
	v_or_b32_e32 v96, 32, v164
	v_mad_u64_u32 v[96:97], s[4:5], v96, s18, 0
	v_add_u32_e32 v97, v97, v2
	v_lshl_add_u64 v[96:97], v[96:97], 1, s[2:3]
	v_lshl_add_u64 v[96:97], v[96:97], 0, v[140:141]
	v_cvt_pk_bf16_f32 v110, v116, v117
	v_cvt_pk_bf16_f32 v111, v118, v119
	v_lshl_add_u64 v[96:97], v[96:97], 0, v[142:143]
	v_cvt_pk_bf16_f32 v80, v80, v81
	v_cvt_pk_bf16_f32 v81, v82, v83
	v_cvt_pk_bf16_f32 v82, v76, v77
	v_cvt_pk_bf16_f32 v83, v78, v79
	global_store_dwordx4 v[112:113], v[108:111], off
	global_store_dwordx4 v[96:97], v[80:83], off offset:256
	v_cvt_pk_bf16_f32 v64, v64, v65
	v_cvt_pk_bf16_f32 v65, v66, v67
	v_or_b32_e32 v80, 48, v164
	v_mad_u64_u32 v[80:81], s[4:5], v80, s18, 0
	v_add_u32_e32 v81, v81, v2
	v_add_u32_e32 v2, 0x80, v164
	v_cvt_pk_bf16_f32 v66, v60, v61
	v_mad_u64_u32 v[60:61], s[4:5], v2, s18, 0
	v_cvt_pk_bf16_f32 v72, v72, v73
	v_cvt_pk_bf16_f32 v73, v74, v75
	v_cvt_pk_bf16_f32 v74, v68, v69
	v_ashrrev_i32_e32 v68, 31, v2
	v_mov_b32_e32 v2, v61
	v_cvt_pk_bf16_f32 v67, v62, v63
	v_mad_u64_u32 v[62:63], s[4:5], v68, s18, v[2:3]
	v_mov_b32_e32 v61, v62
	v_lshl_add_u64 v[80:81], v[80:81], 1, s[2:3]
	v_lshl_add_u64 v[60:61], v[60:61], 1, s[2:3]
	v_lshl_add_u64 v[80:81], v[80:81], 0, v[140:141]
	v_lshl_add_u64 v[60:61], v[60:61], 0, v[140:141]
	v_cvt_pk_bf16_f32 v92, v104, v105
	v_cvt_pk_bf16_f32 v93, v106, v107
	v_cvt_pk_bf16_f32 v94, v100, v101
	v_cvt_pk_bf16_f32 v95, v102, v103
	v_cvt_pk_bf16_f32 v76, v88, v89
	v_cvt_pk_bf16_f32 v77, v90, v91
	v_cvt_pk_bf16_f32 v78, v84, v85
	v_cvt_pk_bf16_f32 v79, v86, v87
	v_lshl_add_u64 v[80:81], v[80:81], 0, v[142:143]
	v_cvt_pk_bf16_f32 v75, v70, v71
	v_lshl_add_u64 v[60:61], v[60:61], 0, v[142:143]
	v_cvt_pk_bf16_f32 v48, v48, v49
	v_cvt_pk_bf16_f32 v49, v50, v51
	v_cvt_pk_bf16_f32 v50, v44, v45
	v_cvt_pk_bf16_f32 v51, v46, v47
	v_add_u32_e32 v2, 0x90, v164
	global_store_dwordx4 v[96:97], v[92:95], off
	global_store_dwordx4 v[80:81], v[76:79], off
	global_store_dwordx4 v[80:81], v[72:75], off offset:256
	global_store_dwordx4 v[60:61], v[48:51], off offset:256
	v_cvt_pk_bf16_f32 v32, v32, v33
	v_cvt_pk_bf16_f32 v33, v34, v35
	v_mad_u64_u32 v[48:49], s[4:5], v2, s18, 0
	v_ashrrev_i32_e32 v50, 31, v2
	v_mov_b32_e32 v2, v49
	v_mad_u64_u32 v[50:51], s[4:5], v50, s18, v[2:3]
	v_mov_b32_e32 v49, v50
	v_lshl_add_u64 v[48:49], v[48:49], 1, s[2:3]
	v_lshl_add_u64 v[48:49], v[48:49], 0, v[140:141]
	v_lshl_add_u64 v[48:49], v[48:49], 0, v[142:143]
	v_cvt_pk_bf16_f32 v34, v28, v29
	v_cvt_pk_bf16_f32 v35, v30, v31
	v_add_u32_e32 v2, 0xa0, v164
	global_store_dwordx4 v[60:61], v[64:67], off
	global_store_dwordx4 v[48:49], v[32:35], off offset:256
	v_cvt_pk_bf16_f32 v44, v56, v57
	v_cvt_pk_bf16_f32 v45, v58, v59
	v_mad_u64_u32 v[32:33], s[4:5], v2, s18, 0
	v_ashrrev_i32_e32 v34, 31, v2
	v_mov_b32_e32 v2, v33
	v_mad_u64_u32 v[34:35], s[4:5], v34, s18, v[2:3]
	v_mov_b32_e32 v33, v34
	v_lshl_add_u64 v[32:33], v[32:33], 1, s[2:3]
	v_lshl_add_u64 v[32:33], v[32:33], 0, v[140:141]
	v_cvt_pk_bf16_f32 v46, v52, v53
	v_cvt_pk_bf16_f32 v47, v54, v55
	v_lshl_add_u64 v[32:33], v[32:33], 0, v[142:143]
	v_cvt_pk_bf16_f32 v16, v16, v17
	v_cvt_pk_bf16_f32 v17, v18, v19
	v_cvt_pk_bf16_f32 v18, v12, v13
	v_cvt_pk_bf16_f32 v19, v14, v15
	v_add_u32_e32 v2, 0xb0, v164
	global_store_dwordx4 v[48:49], v[44:47], off
	global_store_dwordx4 v[32:33], v[16:19], off offset:256
	v_cvt_pk_bf16_f32 v28, v40, v41
	v_cvt_pk_bf16_f32 v29, v42, v43
	v_mad_u64_u32 v[16:17], s[4:5], v2, s18, 0
	v_ashrrev_i32_e32 v18, 31, v2
	v_mov_b32_e32 v2, v17
	v_mad_u64_u32 v[18:19], s[4:5], v18, s18, v[2:3]
	v_mov_b32_e32 v17, v18
	v_lshl_add_u64 v[16:17], v[16:17], 1, s[2:3]
	v_lshl_add_u64 v[16:17], v[16:17], 0, v[140:141]
	v_cvt_pk_bf16_f32 v30, v36, v37
	v_cvt_pk_bf16_f32 v31, v38, v39
	v_cvt_pk_bf16_f32 v12, v24, v25
	v_cvt_pk_bf16_f32 v13, v26, v27
	v_cvt_pk_bf16_f32 v14, v20, v21
	v_cvt_pk_bf16_f32 v15, v22, v23
	v_lshl_add_u64 v[16:17], v[16:17], 0, v[142:143]
	v_cvt_pk_bf16_f32 v8, v8, v9
	v_cvt_pk_bf16_f32 v9, v10, v11
	v_cvt_pk_bf16_f32 v10, v4, v5
	v_cvt_pk_bf16_f32 v11, v6, v7
	s_and_b64 vcc, exec, s[6:7]
	s_mov_b64 s[2:3], s[14:15]
	s_mov_b64 s[16:17], s[12:13]
	s_mov_b64 s[8:9], s[10:11]
	s_mov_b32 s4, s56
	s_mov_b32 s5, s28
	global_store_dwordx4 v[32:33], v[28:31], off
	global_store_dwordx4 v[16:17], v[12:15], off
	global_store_dwordx4 v[16:17], v[8:11], off offset:256
	s_cbranch_vccz .LBB0_726
	s_setprio 0
	s_waitcnt vmcnt(0)
	s_movk_i32 s66, 0x100
	v_cmp_gt_u32_e32 vcc, s66, v135
	s_and_saveexec_b64 s[0:1], vcc
	s_cbranch_execz .LBB0_733
	s_barrier
